# v32: hand-written tile-type-specialised P4 GEMM epilogue; f32 k/v stores permuted by DPP so each store writes whole 128B lines
# baseline (speedup 1.0000x reference)
.LBB0_401:
	s_nop 7
	v_lshl_add_u32 v152, s84, 8, v164
	v_mov_b32_e32 v171, v170
	s_lshl_b32 s46, s6, 9
	s_cmp_gt_i32 s6, 5
	s_cbranch_scc1 .Lepi_pr
	v_mul_u32_u24_e32 v153, 0xc00, v152
	v_lshl_add_u32 v153, v166, 1, v153
	s_add_u32 s86, s8, s46
	s_addc_u32 s87, s9, 0
	s_cmp_lt_i32 s6, 2
	s_cbranch_scc0 .Lepi_kv
	v_pk_mul_f32 v[126:127], v[126:127], v[170:171]
	v_pk_mul_f32 v[128:129], v[128:129], v[170:171]
	v_pk_mul_f32 v[122:123], v[122:123], v[170:171]
	v_pk_mul_f32 v[124:125], v[124:125], v[170:171]
	v_cvt_pk_bf16_f32 v172, v126, v127
	v_cvt_pk_bf16_f32 v173, v128, v129
	v_cvt_pk_bf16_f32 v174, v122, v123
	v_cvt_pk_bf16_f32 v175, v124, v125
	global_store_dwordx4 v153, v[172:175], s[86:87] offset:0
	v_pk_mul_f32 v[118:119], v[118:119], v[170:171]
	v_pk_mul_f32 v[120:121], v[120:121], v[170:171]
	v_pk_mul_f32 v[114:115], v[114:115], v[170:171]
	v_pk_mul_f32 v[116:117], v[116:117], v[170:171]
	v_cvt_pk_bf16_f32 v176, v118, v119
	v_cvt_pk_bf16_f32 v177, v120, v121
	v_cvt_pk_bf16_f32 v178, v114, v115
	v_cvt_pk_bf16_f32 v179, v116, v117
	global_store_dwordx4 v153, v[176:179], s[86:87] offset:256
	s_add_u32 s86, s86, 0xc000
	s_addc_u32 s87, s87, 0
	v_pk_mul_f32 v[110:111], v[110:111], v[170:171]
	v_pk_mul_f32 v[112:113], v[112:113], v[170:171]
	v_pk_mul_f32 v[106:107], v[106:107], v[170:171]
	v_pk_mul_f32 v[108:109], v[108:109], v[170:171]
	v_cvt_pk_bf16_f32 v180, v110, v111
	v_cvt_pk_bf16_f32 v181, v112, v113
	v_cvt_pk_bf16_f32 v182, v106, v107
	v_cvt_pk_bf16_f32 v183, v108, v109
	global_store_dwordx4 v153, v[180:183], s[86:87] offset:0
	v_pk_mul_f32 v[102:103], v[102:103], v[170:171]
	v_pk_mul_f32 v[104:105], v[104:105], v[170:171]
	v_pk_mul_f32 v[98:99], v[98:99], v[170:171]
	v_pk_mul_f32 v[100:101], v[100:101], v[170:171]
	v_cvt_pk_bf16_f32 v184, v102, v103
	v_cvt_pk_bf16_f32 v185, v104, v105
	v_cvt_pk_bf16_f32 v186, v98, v99
	v_cvt_pk_bf16_f32 v187, v100, v101
	global_store_dwordx4 v153, v[184:187], s[86:87] offset:256
	s_add_u32 s86, s86, 0xc000
	s_addc_u32 s87, s87, 0
	v_pk_mul_f32 v[94:95], v[94:95], v[170:171]
	v_pk_mul_f32 v[96:97], v[96:97], v[170:171]
	v_pk_mul_f32 v[90:91], v[90:91], v[170:171]
	v_pk_mul_f32 v[92:93], v[92:93], v[170:171]
	v_cvt_pk_bf16_f32 v172, v94, v95
	v_cvt_pk_bf16_f32 v173, v96, v97
	v_cvt_pk_bf16_f32 v174, v90, v91
	v_cvt_pk_bf16_f32 v175, v92, v93
	global_store_dwordx4 v153, v[172:175], s[86:87] offset:0
	v_pk_mul_f32 v[86:87], v[86:87], v[170:171]
	v_pk_mul_f32 v[88:89], v[88:89], v[170:171]
	v_pk_mul_f32 v[82:83], v[82:83], v[170:171]
	v_pk_mul_f32 v[84:85], v[84:85], v[170:171]
	v_cvt_pk_bf16_f32 v176, v86, v87
	v_cvt_pk_bf16_f32 v177, v88, v89
	v_cvt_pk_bf16_f32 v178, v82, v83
	v_cvt_pk_bf16_f32 v179, v84, v85
	global_store_dwordx4 v153, v[176:179], s[86:87] offset:256
	s_add_u32 s86, s86, 0xc000
	s_addc_u32 s87, s87, 0
	v_pk_mul_f32 v[78:79], v[78:79], v[170:171]
	v_pk_mul_f32 v[80:81], v[80:81], v[170:171]
	v_pk_mul_f32 v[74:75], v[74:75], v[170:171]
	v_pk_mul_f32 v[76:77], v[76:77], v[170:171]
	v_cvt_pk_bf16_f32 v180, v78, v79
	v_cvt_pk_bf16_f32 v181, v80, v81
	v_cvt_pk_bf16_f32 v182, v74, v75
	v_cvt_pk_bf16_f32 v183, v76, v77
	global_store_dwordx4 v153, v[180:183], s[86:87] offset:0
	v_pk_mul_f32 v[70:71], v[70:71], v[170:171]
	v_pk_mul_f32 v[72:73], v[72:73], v[170:171]
	v_pk_mul_f32 v[66:67], v[66:67], v[170:171]
	v_pk_mul_f32 v[68:69], v[68:69], v[170:171]
	v_cvt_pk_bf16_f32 v184, v70, v71
	v_cvt_pk_bf16_f32 v185, v72, v73
	v_cvt_pk_bf16_f32 v186, v66, v67
	v_cvt_pk_bf16_f32 v187, v68, v69
	global_store_dwordx4 v153, v[184:187], s[86:87] offset:256
	s_add_u32 s86, s86, 0x3c000
	s_addc_u32 s87, s87, 0
	v_pk_mul_f32 v[62:63], v[62:63], v[170:171]
	v_pk_mul_f32 v[64:65], v[64:65], v[170:171]
	v_pk_mul_f32 v[58:59], v[58:59], v[170:171]
	v_pk_mul_f32 v[60:61], v[60:61], v[170:171]
	v_cvt_pk_bf16_f32 v172, v62, v63
	v_cvt_pk_bf16_f32 v173, v64, v65
	v_cvt_pk_bf16_f32 v174, v58, v59
	v_cvt_pk_bf16_f32 v175, v60, v61
	global_store_dwordx4 v153, v[172:175], s[86:87] offset:0
	v_pk_mul_f32 v[54:55], v[54:55], v[170:171]
	v_pk_mul_f32 v[56:57], v[56:57], v[170:171]
	v_pk_mul_f32 v[50:51], v[50:51], v[170:171]
	v_pk_mul_f32 v[52:53], v[52:53], v[170:171]
	v_cvt_pk_bf16_f32 v176, v54, v55
	v_cvt_pk_bf16_f32 v177, v56, v57
	v_cvt_pk_bf16_f32 v178, v50, v51
	v_cvt_pk_bf16_f32 v179, v52, v53
	global_store_dwordx4 v153, v[176:179], s[86:87] offset:256
	s_add_u32 s86, s86, 0xc000
	s_addc_u32 s87, s87, 0
	v_pk_mul_f32 v[46:47], v[46:47], v[170:171]
	v_pk_mul_f32 v[48:49], v[48:49], v[170:171]
	v_pk_mul_f32 v[42:43], v[42:43], v[170:171]
	v_pk_mul_f32 v[44:45], v[44:45], v[170:171]
	v_cvt_pk_bf16_f32 v180, v46, v47
	v_cvt_pk_bf16_f32 v181, v48, v49
	v_cvt_pk_bf16_f32 v182, v42, v43
	v_cvt_pk_bf16_f32 v183, v44, v45
	global_store_dwordx4 v153, v[180:183], s[86:87] offset:0
	v_pk_mul_f32 v[38:39], v[38:39], v[170:171]
	v_pk_mul_f32 v[40:41], v[40:41], v[170:171]
	v_pk_mul_f32 v[34:35], v[34:35], v[170:171]
	v_pk_mul_f32 v[36:37], v[36:37], v[170:171]
	v_cvt_pk_bf16_f32 v184, v38, v39
	v_cvt_pk_bf16_f32 v185, v40, v41
	v_cvt_pk_bf16_f32 v186, v34, v35
	v_cvt_pk_bf16_f32 v187, v36, v37
	global_store_dwordx4 v153, v[184:187], s[86:87] offset:256
	s_add_u32 s86, s86, 0xc000
	s_addc_u32 s87, s87, 0
	v_pk_mul_f32 v[30:31], v[30:31], v[170:171]
	v_pk_mul_f32 v[32:33], v[32:33], v[170:171]
	v_pk_mul_f32 v[26:27], v[26:27], v[170:171]
	v_pk_mul_f32 v[28:29], v[28:29], v[170:171]
	v_cvt_pk_bf16_f32 v172, v30, v31
	v_cvt_pk_bf16_f32 v173, v32, v33
	v_cvt_pk_bf16_f32 v174, v26, v27
	v_cvt_pk_bf16_f32 v175, v28, v29
	global_store_dwordx4 v153, v[172:175], s[86:87] offset:0
	v_pk_mul_f32 v[22:23], v[22:23], v[170:171]
	v_pk_mul_f32 v[24:25], v[24:25], v[170:171]
	v_pk_mul_f32 v[18:19], v[18:19], v[170:171]
	v_pk_mul_f32 v[20:21], v[20:21], v[170:171]
	v_cvt_pk_bf16_f32 v176, v22, v23
	v_cvt_pk_bf16_f32 v177, v24, v25
	v_cvt_pk_bf16_f32 v178, v18, v19
	v_cvt_pk_bf16_f32 v179, v20, v21
	global_store_dwordx4 v153, v[176:179], s[86:87] offset:256
	s_add_u32 s86, s86, 0xc000
	s_addc_u32 s87, s87, 0
	v_pk_mul_f32 v[14:15], v[14:15], v[170:171]
	v_pk_mul_f32 v[16:17], v[16:17], v[170:171]
	v_pk_mul_f32 v[10:11], v[10:11], v[170:171]
	v_pk_mul_f32 v[12:13], v[12:13], v[170:171]
	v_cvt_pk_bf16_f32 v180, v14, v15
	v_cvt_pk_bf16_f32 v181, v16, v17
	v_cvt_pk_bf16_f32 v182, v10, v11
	v_cvt_pk_bf16_f32 v183, v12, v13
	global_store_dwordx4 v153, v[180:183], s[86:87] offset:0
	v_pk_mul_f32 v[6:7], v[6:7], v[170:171]
	v_pk_mul_f32 v[8:9], v[8:9], v[170:171]
	v_pk_mul_f32 v[2:3], v[2:3], v[170:171]
	v_pk_mul_f32 v[4:5], v[4:5], v[170:171]
	v_cvt_pk_bf16_f32 v184, v6, v7
	v_cvt_pk_bf16_f32 v185, v8, v9
	v_cvt_pk_bf16_f32 v186, v2, v3
	v_cvt_pk_bf16_f32 v187, v4, v5
	global_store_dwordx4 v153, v[184:187], s[86:87] offset:256
	s_branch .Lepi_done
.Lepi_kv:
	s_cmp_gt_u32 s6, 3
	s_cselect_b32 s88, s14, s12
	s_cselect_b32 s89, s15, s13
	s_cselect_b32 s48, s18, s16
	s_cselect_b32 s49, s19, s17
	s_cmp_gt_i32 s84, 63
	s_cselect_b32 s88, s48, s88
	s_cselect_b32 s89, s49, s89
	s_cselect_b32 s48, 0x2000000, 0
	s_sub_u32 s88, s88, s48
	s_subb_u32 s89, s89, 0
	s_and_b32 s48, s6, 1
	s_lshl_b32 s48, s48, 10
	s_add_u32 s88, s88, s48
	s_addc_u32 s89, s89, 0
	v_lshlrev_b32_e32 v154, 11, v152
	v_lshl_add_u32 v154, v166, 2, v154
	v_and_b32_e32 v157, 8, v164
	v_mul_u32_u24_e32 v157, 0x7fe, v157
	v_sub_u32_e32 v154, v154, v157
	v_add_u32_e32 v155, 0x4000, v154
	v_cvt_pk_bf16_f32 v172, v126, v127
	v_cvt_pk_bf16_f32 v173, v128, v129
	v_cvt_pk_bf16_f32 v174, v122, v123
	v_cvt_pk_bf16_f32 v175, v124, v125
	global_store_dwordx4 v153, v[172:175], s[86:87] offset:0
	v_mov_b32_e32 v188, v126
	v_mov_b32_e32 v189, v127
	v_mov_b32_e32 v190, v128
	v_mov_b32_e32 v191, v129
	v_mov_b32_dpp v126, v122 row_ror:8 row_mask:0xf bank_mask:0xc
	v_mov_b32_dpp v127, v123 row_ror:8 row_mask:0xf bank_mask:0xc
	v_mov_b32_dpp v128, v124 row_ror:8 row_mask:0xf bank_mask:0xc
	v_mov_b32_dpp v129, v125 row_ror:8 row_mask:0xf bank_mask:0xc
	v_mov_b32_dpp v122, v188 row_ror:8 row_mask:0xf bank_mask:0x3
	v_mov_b32_dpp v123, v189 row_ror:8 row_mask:0xf bank_mask:0x3
	v_mov_b32_dpp v124, v190 row_ror:8 row_mask:0xf bank_mask:0x3
	v_mov_b32_dpp v125, v191 row_ror:8 row_mask:0xf bank_mask:0x3
	global_store_dwordx4 v154, v[126:129], s[88:89] offset:0
	global_store_dwordx4 v155, v[122:125], s[88:89] offset:0
	v_cvt_pk_bf16_f32 v176, v118, v119
	v_cvt_pk_bf16_f32 v177, v120, v121
	v_cvt_pk_bf16_f32 v178, v114, v115
	v_cvt_pk_bf16_f32 v179, v116, v117
	global_store_dwordx4 v153, v[176:179], s[86:87] offset:256
	v_mov_b32_e32 v192, v118
	v_mov_b32_e32 v193, v119
	v_mov_b32_e32 v194, v120
	v_mov_b32_e32 v195, v121
	v_mov_b32_dpp v118, v114 row_ror:8 row_mask:0xf bank_mask:0xc
	v_mov_b32_dpp v119, v115 row_ror:8 row_mask:0xf bank_mask:0xc
	v_mov_b32_dpp v120, v116 row_ror:8 row_mask:0xf bank_mask:0xc
	v_mov_b32_dpp v121, v117 row_ror:8 row_mask:0xf bank_mask:0xc
	v_mov_b32_dpp v114, v192 row_ror:8 row_mask:0xf bank_mask:0x3
	v_mov_b32_dpp v115, v193 row_ror:8 row_mask:0xf bank_mask:0x3
	v_mov_b32_dpp v116, v194 row_ror:8 row_mask:0xf bank_mask:0x3
	v_mov_b32_dpp v117, v195 row_ror:8 row_mask:0xf bank_mask:0x3
	global_store_dwordx4 v154, v[118:121], s[88:89] offset:512
	global_store_dwordx4 v155, v[114:117], s[88:89] offset:512
	s_add_u32 s86, s86, 0xc000
	s_addc_u32 s87, s87, 0
	s_add_u32 s88, s88, 0x8000
	s_addc_u32 s89, s89, 0
	v_cvt_pk_bf16_f32 v180, v110, v111
	v_cvt_pk_bf16_f32 v181, v112, v113
	v_cvt_pk_bf16_f32 v182, v106, v107
	v_cvt_pk_bf16_f32 v183, v108, v109
	global_store_dwordx4 v153, v[180:183], s[86:87] offset:0
	v_mov_b32_e32 v188, v110
	v_mov_b32_e32 v189, v111
	v_mov_b32_e32 v190, v112
	v_mov_b32_e32 v191, v113
	v_mov_b32_dpp v110, v106 row_ror:8 row_mask:0xf bank_mask:0xc
	v_mov_b32_dpp v111, v107 row_ror:8 row_mask:0xf bank_mask:0xc
	v_mov_b32_dpp v112, v108 row_ror:8 row_mask:0xf bank_mask:0xc
	v_mov_b32_dpp v113, v109 row_ror:8 row_mask:0xf bank_mask:0xc
	v_mov_b32_dpp v106, v188 row_ror:8 row_mask:0xf bank_mask:0x3
	v_mov_b32_dpp v107, v189 row_ror:8 row_mask:0xf bank_mask:0x3
	v_mov_b32_dpp v108, v190 row_ror:8 row_mask:0xf bank_mask:0x3
	v_mov_b32_dpp v109, v191 row_ror:8 row_mask:0xf bank_mask:0x3
	global_store_dwordx4 v154, v[110:113], s[88:89] offset:0
	global_store_dwordx4 v155, v[106:109], s[88:89] offset:0
	v_cvt_pk_bf16_f32 v184, v102, v103
	v_cvt_pk_bf16_f32 v185, v104, v105
	v_cvt_pk_bf16_f32 v186, v98, v99
	v_cvt_pk_bf16_f32 v187, v100, v101
	global_store_dwordx4 v153, v[184:187], s[86:87] offset:256
	v_mov_b32_e32 v192, v102
	v_mov_b32_e32 v193, v103
	v_mov_b32_e32 v194, v104
	v_mov_b32_e32 v195, v105
	v_mov_b32_dpp v102, v98 row_ror:8 row_mask:0xf bank_mask:0xc
	v_mov_b32_dpp v103, v99 row_ror:8 row_mask:0xf bank_mask:0xc
	v_mov_b32_dpp v104, v100 row_ror:8 row_mask:0xf bank_mask:0xc
	v_mov_b32_dpp v105, v101 row_ror:8 row_mask:0xf bank_mask:0xc
	v_mov_b32_dpp v98, v192 row_ror:8 row_mask:0xf bank_mask:0x3
	v_mov_b32_dpp v99, v193 row_ror:8 row_mask:0xf bank_mask:0x3
	v_mov_b32_dpp v100, v194 row_ror:8 row_mask:0xf bank_mask:0x3
	v_mov_b32_dpp v101, v195 row_ror:8 row_mask:0xf bank_mask:0x3
	global_store_dwordx4 v154, v[102:105], s[88:89] offset:512
	global_store_dwordx4 v155, v[98:101], s[88:89] offset:512
	s_add_u32 s86, s86, 0xc000
	s_addc_u32 s87, s87, 0
	s_add_u32 s88, s88, 0x8000
	s_addc_u32 s89, s89, 0
	v_cvt_pk_bf16_f32 v172, v94, v95
	v_cvt_pk_bf16_f32 v173, v96, v97
	v_cvt_pk_bf16_f32 v174, v90, v91
	v_cvt_pk_bf16_f32 v175, v92, v93
	global_store_dwordx4 v153, v[172:175], s[86:87] offset:0
	v_mov_b32_e32 v188, v94
	v_mov_b32_e32 v189, v95
	v_mov_b32_e32 v190, v96
	v_mov_b32_e32 v191, v97
	v_mov_b32_dpp v94, v90 row_ror:8 row_mask:0xf bank_mask:0xc
	v_mov_b32_dpp v95, v91 row_ror:8 row_mask:0xf bank_mask:0xc
	v_mov_b32_dpp v96, v92 row_ror:8 row_mask:0xf bank_mask:0xc
	v_mov_b32_dpp v97, v93 row_ror:8 row_mask:0xf bank_mask:0xc
	v_mov_b32_dpp v90, v188 row_ror:8 row_mask:0xf bank_mask:0x3
	v_mov_b32_dpp v91, v189 row_ror:8 row_mask:0xf bank_mask:0x3
	v_mov_b32_dpp v92, v190 row_ror:8 row_mask:0xf bank_mask:0x3
	v_mov_b32_dpp v93, v191 row_ror:8 row_mask:0xf bank_mask:0x3
	global_store_dwordx4 v154, v[94:97], s[88:89] offset:0
	global_store_dwordx4 v155, v[90:93], s[88:89] offset:0
	v_cvt_pk_bf16_f32 v176, v86, v87
	v_cvt_pk_bf16_f32 v177, v88, v89
	v_cvt_pk_bf16_f32 v178, v82, v83
	v_cvt_pk_bf16_f32 v179, v84, v85
	global_store_dwordx4 v153, v[176:179], s[86:87] offset:256
	v_mov_b32_e32 v192, v86
	v_mov_b32_e32 v193, v87
	v_mov_b32_e32 v194, v88
	v_mov_b32_e32 v195, v89
	v_mov_b32_dpp v86, v82 row_ror:8 row_mask:0xf bank_mask:0xc
	v_mov_b32_dpp v87, v83 row_ror:8 row_mask:0xf bank_mask:0xc
	v_mov_b32_dpp v88, v84 row_ror:8 row_mask:0xf bank_mask:0xc
	v_mov_b32_dpp v89, v85 row_ror:8 row_mask:0xf bank_mask:0xc
	v_mov_b32_dpp v82, v192 row_ror:8 row_mask:0xf bank_mask:0x3
	v_mov_b32_dpp v83, v193 row_ror:8 row_mask:0xf bank_mask:0x3
	v_mov_b32_dpp v84, v194 row_ror:8 row_mask:0xf bank_mask:0x3
	v_mov_b32_dpp v85, v195 row_ror:8 row_mask:0xf bank_mask:0x3
	global_store_dwordx4 v154, v[86:89], s[88:89] offset:512
	global_store_dwordx4 v155, v[82:85], s[88:89] offset:512
	s_add_u32 s86, s86, 0xc000
	s_addc_u32 s87, s87, 0
	s_add_u32 s88, s88, 0x8000
	s_addc_u32 s89, s89, 0
	v_cvt_pk_bf16_f32 v180, v78, v79
	v_cvt_pk_bf16_f32 v181, v80, v81
	v_cvt_pk_bf16_f32 v182, v74, v75
	v_cvt_pk_bf16_f32 v183, v76, v77
	global_store_dwordx4 v153, v[180:183], s[86:87] offset:0
	v_mov_b32_e32 v188, v78
	v_mov_b32_e32 v189, v79
	v_mov_b32_e32 v190, v80
	v_mov_b32_e32 v191, v81
	v_mov_b32_dpp v78, v74 row_ror:8 row_mask:0xf bank_mask:0xc
	v_mov_b32_dpp v79, v75 row_ror:8 row_mask:0xf bank_mask:0xc
	v_mov_b32_dpp v80, v76 row_ror:8 row_mask:0xf bank_mask:0xc
	v_mov_b32_dpp v81, v77 row_ror:8 row_mask:0xf bank_mask:0xc
	v_mov_b32_dpp v74, v188 row_ror:8 row_mask:0xf bank_mask:0x3
	v_mov_b32_dpp v75, v189 row_ror:8 row_mask:0xf bank_mask:0x3
	v_mov_b32_dpp v76, v190 row_ror:8 row_mask:0xf bank_mask:0x3
	v_mov_b32_dpp v77, v191 row_ror:8 row_mask:0xf bank_mask:0x3
	global_store_dwordx4 v154, v[78:81], s[88:89] offset:0
	global_store_dwordx4 v155, v[74:77], s[88:89] offset:0
	v_cvt_pk_bf16_f32 v184, v70, v71
	v_cvt_pk_bf16_f32 v185, v72, v73
	v_cvt_pk_bf16_f32 v186, v66, v67
	v_cvt_pk_bf16_f32 v187, v68, v69
	global_store_dwordx4 v153, v[184:187], s[86:87] offset:256
	v_mov_b32_e32 v192, v70
	v_mov_b32_e32 v193, v71
	v_mov_b32_e32 v194, v72
	v_mov_b32_e32 v195, v73
	v_mov_b32_dpp v70, v66 row_ror:8 row_mask:0xf bank_mask:0xc
	v_mov_b32_dpp v71, v67 row_ror:8 row_mask:0xf bank_mask:0xc
	v_mov_b32_dpp v72, v68 row_ror:8 row_mask:0xf bank_mask:0xc
	v_mov_b32_dpp v73, v69 row_ror:8 row_mask:0xf bank_mask:0xc
	v_mov_b32_dpp v66, v192 row_ror:8 row_mask:0xf bank_mask:0x3
	v_mov_b32_dpp v67, v193 row_ror:8 row_mask:0xf bank_mask:0x3
	v_mov_b32_dpp v68, v194 row_ror:8 row_mask:0xf bank_mask:0x3
	v_mov_b32_dpp v69, v195 row_ror:8 row_mask:0xf bank_mask:0x3
	global_store_dwordx4 v154, v[70:73], s[88:89] offset:512
	global_store_dwordx4 v155, v[66:69], s[88:89] offset:512
	s_add_u32 s86, s86, 0x3c000
	s_addc_u32 s87, s87, 0
	s_add_u32 s88, s88, 0x28000
	s_addc_u32 s89, s89, 0
	v_cvt_pk_bf16_f32 v172, v62, v63
	v_cvt_pk_bf16_f32 v173, v64, v65
	v_cvt_pk_bf16_f32 v174, v58, v59
	v_cvt_pk_bf16_f32 v175, v60, v61
	global_store_dwordx4 v153, v[172:175], s[86:87] offset:0
	v_mov_b32_e32 v188, v62
	v_mov_b32_e32 v189, v63
	v_mov_b32_e32 v190, v64
	v_mov_b32_e32 v191, v65
	v_mov_b32_dpp v62, v58 row_ror:8 row_mask:0xf bank_mask:0xc
	v_mov_b32_dpp v63, v59 row_ror:8 row_mask:0xf bank_mask:0xc
	v_mov_b32_dpp v64, v60 row_ror:8 row_mask:0xf bank_mask:0xc
	v_mov_b32_dpp v65, v61 row_ror:8 row_mask:0xf bank_mask:0xc
	v_mov_b32_dpp v58, v188 row_ror:8 row_mask:0xf bank_mask:0x3
	v_mov_b32_dpp v59, v189 row_ror:8 row_mask:0xf bank_mask:0x3
	v_mov_b32_dpp v60, v190 row_ror:8 row_mask:0xf bank_mask:0x3
	v_mov_b32_dpp v61, v191 row_ror:8 row_mask:0xf bank_mask:0x3
	global_store_dwordx4 v154, v[62:65], s[88:89] offset:0
	global_store_dwordx4 v155, v[58:61], s[88:89] offset:0
	v_cvt_pk_bf16_f32 v176, v54, v55
	v_cvt_pk_bf16_f32 v177, v56, v57
	v_cvt_pk_bf16_f32 v178, v50, v51
	v_cvt_pk_bf16_f32 v179, v52, v53
	global_store_dwordx4 v153, v[176:179], s[86:87] offset:256
	v_mov_b32_e32 v192, v54
	v_mov_b32_e32 v193, v55
	v_mov_b32_e32 v194, v56
	v_mov_b32_e32 v195, v57
	v_mov_b32_dpp v54, v50 row_ror:8 row_mask:0xf bank_mask:0xc
	v_mov_b32_dpp v55, v51 row_ror:8 row_mask:0xf bank_mask:0xc
	v_mov_b32_dpp v56, v52 row_ror:8 row_mask:0xf bank_mask:0xc
	v_mov_b32_dpp v57, v53 row_ror:8 row_mask:0xf bank_mask:0xc
	v_mov_b32_dpp v50, v192 row_ror:8 row_mask:0xf bank_mask:0x3
	v_mov_b32_dpp v51, v193 row_ror:8 row_mask:0xf bank_mask:0x3
	v_mov_b32_dpp v52, v194 row_ror:8 row_mask:0xf bank_mask:0x3
	v_mov_b32_dpp v53, v195 row_ror:8 row_mask:0xf bank_mask:0x3
	global_store_dwordx4 v154, v[54:57], s[88:89] offset:512
	global_store_dwordx4 v155, v[50:53], s[88:89] offset:512
	s_add_u32 s86, s86, 0xc000
	s_addc_u32 s87, s87, 0
	s_add_u32 s88, s88, 0x8000
	s_addc_u32 s89, s89, 0
	v_cvt_pk_bf16_f32 v180, v46, v47
	v_cvt_pk_bf16_f32 v181, v48, v49
	v_cvt_pk_bf16_f32 v182, v42, v43
	v_cvt_pk_bf16_f32 v183, v44, v45
	global_store_dwordx4 v153, v[180:183], s[86:87] offset:0
	v_mov_b32_e32 v188, v46
	v_mov_b32_e32 v189, v47
	v_mov_b32_e32 v190, v48
	v_mov_b32_e32 v191, v49
	v_mov_b32_dpp v46, v42 row_ror:8 row_mask:0xf bank_mask:0xc
	v_mov_b32_dpp v47, v43 row_ror:8 row_mask:0xf bank_mask:0xc
	v_mov_b32_dpp v48, v44 row_ror:8 row_mask:0xf bank_mask:0xc
	v_mov_b32_dpp v49, v45 row_ror:8 row_mask:0xf bank_mask:0xc
	v_mov_b32_dpp v42, v188 row_ror:8 row_mask:0xf bank_mask:0x3
	v_mov_b32_dpp v43, v189 row_ror:8 row_mask:0xf bank_mask:0x3
	v_mov_b32_dpp v44, v190 row_ror:8 row_mask:0xf bank_mask:0x3
	v_mov_b32_dpp v45, v191 row_ror:8 row_mask:0xf bank_mask:0x3
	global_store_dwordx4 v154, v[46:49], s[88:89] offset:0
	global_store_dwordx4 v155, v[42:45], s[88:89] offset:0
	v_cvt_pk_bf16_f32 v184, v38, v39
	v_cvt_pk_bf16_f32 v185, v40, v41
	v_cvt_pk_bf16_f32 v186, v34, v35
	v_cvt_pk_bf16_f32 v187, v36, v37
	global_store_dwordx4 v153, v[184:187], s[86:87] offset:256
	v_mov_b32_e32 v192, v38
	v_mov_b32_e32 v193, v39
	v_mov_b32_e32 v194, v40
	v_mov_b32_e32 v195, v41
	v_mov_b32_dpp v38, v34 row_ror:8 row_mask:0xf bank_mask:0xc
	v_mov_b32_dpp v39, v35 row_ror:8 row_mask:0xf bank_mask:0xc
	v_mov_b32_dpp v40, v36 row_ror:8 row_mask:0xf bank_mask:0xc
	v_mov_b32_dpp v41, v37 row_ror:8 row_mask:0xf bank_mask:0xc
	v_mov_b32_dpp v34, v192 row_ror:8 row_mask:0xf bank_mask:0x3
	v_mov_b32_dpp v35, v193 row_ror:8 row_mask:0xf bank_mask:0x3
	v_mov_b32_dpp v36, v194 row_ror:8 row_mask:0xf bank_mask:0x3
	v_mov_b32_dpp v37, v195 row_ror:8 row_mask:0xf bank_mask:0x3
	global_store_dwordx4 v154, v[38:41], s[88:89] offset:512
	global_store_dwordx4 v155, v[34:37], s[88:89] offset:512
	s_add_u32 s86, s86, 0xc000
	s_addc_u32 s87, s87, 0
	s_add_u32 s88, s88, 0x8000
	s_addc_u32 s89, s89, 0
	v_cvt_pk_bf16_f32 v172, v30, v31
	v_cvt_pk_bf16_f32 v173, v32, v33
	v_cvt_pk_bf16_f32 v174, v26, v27
	v_cvt_pk_bf16_f32 v175, v28, v29
	global_store_dwordx4 v153, v[172:175], s[86:87] offset:0
	v_mov_b32_e32 v188, v30
	v_mov_b32_e32 v189, v31
	v_mov_b32_e32 v190, v32
	v_mov_b32_e32 v191, v33
	v_mov_b32_dpp v30, v26 row_ror:8 row_mask:0xf bank_mask:0xc
	v_mov_b32_dpp v31, v27 row_ror:8 row_mask:0xf bank_mask:0xc
	v_mov_b32_dpp v32, v28 row_ror:8 row_mask:0xf bank_mask:0xc
	v_mov_b32_dpp v33, v29 row_ror:8 row_mask:0xf bank_mask:0xc
	v_mov_b32_dpp v26, v188 row_ror:8 row_mask:0xf bank_mask:0x3
	v_mov_b32_dpp v27, v189 row_ror:8 row_mask:0xf bank_mask:0x3
	v_mov_b32_dpp v28, v190 row_ror:8 row_mask:0xf bank_mask:0x3
	v_mov_b32_dpp v29, v191 row_ror:8 row_mask:0xf bank_mask:0x3
	global_store_dwordx4 v154, v[30:33], s[88:89] offset:0
	global_store_dwordx4 v155, v[26:29], s[88:89] offset:0
	v_cvt_pk_bf16_f32 v176, v22, v23
	v_cvt_pk_bf16_f32 v177, v24, v25
	v_cvt_pk_bf16_f32 v178, v18, v19
	v_cvt_pk_bf16_f32 v179, v20, v21
	global_store_dwordx4 v153, v[176:179], s[86:87] offset:256
	v_mov_b32_e32 v192, v22
	v_mov_b32_e32 v193, v23
	v_mov_b32_e32 v194, v24
	v_mov_b32_e32 v195, v25
	v_mov_b32_dpp v22, v18 row_ror:8 row_mask:0xf bank_mask:0xc
	v_mov_b32_dpp v23, v19 row_ror:8 row_mask:0xf bank_mask:0xc
	v_mov_b32_dpp v24, v20 row_ror:8 row_mask:0xf bank_mask:0xc
	v_mov_b32_dpp v25, v21 row_ror:8 row_mask:0xf bank_mask:0xc
	v_mov_b32_dpp v18, v192 row_ror:8 row_mask:0xf bank_mask:0x3
	v_mov_b32_dpp v19, v193 row_ror:8 row_mask:0xf bank_mask:0x3
	v_mov_b32_dpp v20, v194 row_ror:8 row_mask:0xf bank_mask:0x3
	v_mov_b32_dpp v21, v195 row_ror:8 row_mask:0xf bank_mask:0x3
	global_store_dwordx4 v154, v[22:25], s[88:89] offset:512
	global_store_dwordx4 v155, v[18:21], s[88:89] offset:512
	s_add_u32 s86, s86, 0xc000
	s_addc_u32 s87, s87, 0
	s_add_u32 s88, s88, 0x8000
	s_addc_u32 s89, s89, 0
	v_cvt_pk_bf16_f32 v180, v14, v15
	v_cvt_pk_bf16_f32 v181, v16, v17
	v_cvt_pk_bf16_f32 v182, v10, v11
	v_cvt_pk_bf16_f32 v183, v12, v13
	global_store_dwordx4 v153, v[180:183], s[86:87] offset:0
	v_mov_b32_e32 v188, v14
	v_mov_b32_e32 v189, v15
	v_mov_b32_e32 v190, v16
	v_mov_b32_e32 v191, v17
	v_mov_b32_dpp v14, v10 row_ror:8 row_mask:0xf bank_mask:0xc
	v_mov_b32_dpp v15, v11 row_ror:8 row_mask:0xf bank_mask:0xc
	v_mov_b32_dpp v16, v12 row_ror:8 row_mask:0xf bank_mask:0xc
	v_mov_b32_dpp v17, v13 row_ror:8 row_mask:0xf bank_mask:0xc
	v_mov_b32_dpp v10, v188 row_ror:8 row_mask:0xf bank_mask:0x3
	v_mov_b32_dpp v11, v189 row_ror:8 row_mask:0xf bank_mask:0x3
	v_mov_b32_dpp v12, v190 row_ror:8 row_mask:0xf bank_mask:0x3
	v_mov_b32_dpp v13, v191 row_ror:8 row_mask:0xf bank_mask:0x3
	global_store_dwordx4 v154, v[14:17], s[88:89] offset:0
	global_store_dwordx4 v155, v[10:13], s[88:89] offset:0
	v_cvt_pk_bf16_f32 v184, v6, v7
	v_cvt_pk_bf16_f32 v185, v8, v9
	v_cvt_pk_bf16_f32 v186, v2, v3
	v_cvt_pk_bf16_f32 v187, v4, v5
	global_store_dwordx4 v153, v[184:187], s[86:87] offset:256
	v_mov_b32_e32 v192, v6
	v_mov_b32_e32 v193, v7
	v_mov_b32_e32 v194, v8
	v_mov_b32_e32 v195, v9
	v_mov_b32_dpp v6, v2 row_ror:8 row_mask:0xf bank_mask:0xc
	v_mov_b32_dpp v7, v3 row_ror:8 row_mask:0xf bank_mask:0xc
	v_mov_b32_dpp v8, v4 row_ror:8 row_mask:0xf bank_mask:0xc
	v_mov_b32_dpp v9, v5 row_ror:8 row_mask:0xf bank_mask:0xc
	v_mov_b32_dpp v2, v192 row_ror:8 row_mask:0xf bank_mask:0x3
	v_mov_b32_dpp v3, v193 row_ror:8 row_mask:0xf bank_mask:0x3
	v_mov_b32_dpp v4, v194 row_ror:8 row_mask:0xf bank_mask:0x3
	v_mov_b32_dpp v5, v195 row_ror:8 row_mask:0xf bank_mask:0x3
	global_store_dwordx4 v154, v[6:9], s[88:89] offset:512
	global_store_dwordx4 v155, v[2:5], s[88:89] offset:512
	s_branch .Lepi_done
.Lepi_pr:
	v_mul_u32_u24_e32 v153, 0xe00, v152
	v_lshl_add_u32 v153, v166, 1, v153
	s_add_u32 s86, s10, s46
	s_addc_u32 s87, s11, 0
	s_sub_u32 s86, s86, 0xc00
	s_subb_u32 s87, s87, 0
	s_lshl_b32 s46, s6, 10
	v_lshlrev_b32_e32 v156, 2, v166
	s_cmp_gt_i32 s84, 63
	s_cbranch_scc1 .Lepi_prs
	v_cvt_pk_bf16_f32 v172, v126, v127
	v_cvt_pk_bf16_f32 v173, v128, v129
	v_cvt_pk_bf16_f32 v174, v122, v123
	v_cvt_pk_bf16_f32 v175, v124, v125
	global_store_dwordx4 v153, v[172:175], s[86:87] offset:0
	v_cvt_pk_bf16_f32 v176, v118, v119
	v_cvt_pk_bf16_f32 v177, v120, v121
	v_cvt_pk_bf16_f32 v178, v114, v115
	v_cvt_pk_bf16_f32 v179, v116, v117
	global_store_dwordx4 v153, v[176:179], s[86:87] offset:256
	s_add_u32 s86, s86, 0xe000
	s_addc_u32 s87, s87, 0
	v_cvt_pk_bf16_f32 v180, v110, v111
	v_cvt_pk_bf16_f32 v181, v112, v113
	v_cvt_pk_bf16_f32 v182, v106, v107
	v_cvt_pk_bf16_f32 v183, v108, v109
	global_store_dwordx4 v153, v[180:183], s[86:87] offset:0
	v_cvt_pk_bf16_f32 v184, v102, v103
	v_cvt_pk_bf16_f32 v185, v104, v105
	v_cvt_pk_bf16_f32 v186, v98, v99
	v_cvt_pk_bf16_f32 v187, v100, v101
	global_store_dwordx4 v153, v[184:187], s[86:87] offset:256
	s_add_u32 s86, s86, 0xe000
	s_addc_u32 s87, s87, 0
	v_cvt_pk_bf16_f32 v172, v94, v95
	v_cvt_pk_bf16_f32 v173, v96, v97
	v_cvt_pk_bf16_f32 v174, v90, v91
	v_cvt_pk_bf16_f32 v175, v92, v93
	global_store_dwordx4 v153, v[172:175], s[86:87] offset:0
	v_cvt_pk_bf16_f32 v176, v86, v87
	v_cvt_pk_bf16_f32 v177, v88, v89
	v_cvt_pk_bf16_f32 v178, v82, v83
	v_cvt_pk_bf16_f32 v179, v84, v85
	global_store_dwordx4 v153, v[176:179], s[86:87] offset:256
	s_add_u32 s86, s86, 0xe000
	s_addc_u32 s87, s87, 0
	v_cvt_pk_bf16_f32 v180, v78, v79
	v_cvt_pk_bf16_f32 v181, v80, v81
	v_cvt_pk_bf16_f32 v182, v74, v75
	v_cvt_pk_bf16_f32 v183, v76, v77
	global_store_dwordx4 v153, v[180:183], s[86:87] offset:0
	v_cvt_pk_bf16_f32 v184, v70, v71
	v_cvt_pk_bf16_f32 v185, v72, v73
	v_cvt_pk_bf16_f32 v186, v66, v67
	v_cvt_pk_bf16_f32 v187, v68, v69
	global_store_dwordx4 v153, v[184:187], s[86:87] offset:256
	s_add_u32 s86, s86, 0x46000
	s_addc_u32 s87, s87, 0
	v_cvt_pk_bf16_f32 v172, v62, v63
	v_cvt_pk_bf16_f32 v173, v64, v65
	v_cvt_pk_bf16_f32 v174, v58, v59
	v_cvt_pk_bf16_f32 v175, v60, v61
	global_store_dwordx4 v153, v[172:175], s[86:87] offset:0
	v_cvt_pk_bf16_f32 v176, v54, v55
	v_cvt_pk_bf16_f32 v177, v56, v57
	v_cvt_pk_bf16_f32 v178, v50, v51
	v_cvt_pk_bf16_f32 v179, v52, v53
	global_store_dwordx4 v153, v[176:179], s[86:87] offset:256
	s_add_u32 s86, s86, 0xe000
	s_addc_u32 s87, s87, 0
	v_cvt_pk_bf16_f32 v180, v46, v47
	v_cvt_pk_bf16_f32 v181, v48, v49
	v_cvt_pk_bf16_f32 v182, v42, v43
	v_cvt_pk_bf16_f32 v183, v44, v45
	global_store_dwordx4 v153, v[180:183], s[86:87] offset:0
	v_cvt_pk_bf16_f32 v184, v38, v39
	v_cvt_pk_bf16_f32 v185, v40, v41
	v_cvt_pk_bf16_f32 v186, v34, v35
	v_cvt_pk_bf16_f32 v187, v36, v37
	global_store_dwordx4 v153, v[184:187], s[86:87] offset:256
	s_add_u32 s86, s86, 0xe000
	s_addc_u32 s87, s87, 0
	v_cvt_pk_bf16_f32 v172, v30, v31
	v_cvt_pk_bf16_f32 v173, v32, v33
	v_cvt_pk_bf16_f32 v174, v26, v27
	v_cvt_pk_bf16_f32 v175, v28, v29
	global_store_dwordx4 v153, v[172:175], s[86:87] offset:0
	v_cvt_pk_bf16_f32 v176, v22, v23
	v_cvt_pk_bf16_f32 v177, v24, v25
	v_cvt_pk_bf16_f32 v178, v18, v19
	v_cvt_pk_bf16_f32 v179, v20, v21
	global_store_dwordx4 v153, v[176:179], s[86:87] offset:256
	s_add_u32 s86, s86, 0xe000
	s_addc_u32 s87, s87, 0
	v_cvt_pk_bf16_f32 v180, v14, v15
	v_cvt_pk_bf16_f32 v181, v16, v17
	v_cvt_pk_bf16_f32 v182, v10, v11
	v_cvt_pk_bf16_f32 v183, v12, v13
	global_store_dwordx4 v153, v[180:183], s[86:87] offset:0
	v_cvt_pk_bf16_f32 v184, v6, v7
	v_cvt_pk_bf16_f32 v185, v8, v9
	v_cvt_pk_bf16_f32 v186, v2, v3
	v_cvt_pk_bf16_f32 v187, v4, v5
	global_store_dwordx4 v153, v[184:187], s[86:87] offset:256
	s_and_b32 s47, s84, 7
	s_cmp_eq_u32 s47, 7
	s_cbranch_scc0 .Lepi_done
	s_and_b64 vcc, exec, s[0:1]
	s_cbranch_vccz .Lepi_done
	s_lshr_b32 s47, s84, 3
	s_mul_i32 s47, s47, 0x1c00
	s_add_i32 s47, s47, s46
	s_add_u32 s88, s20, s47
	s_addc_u32 s89, s21, 0
	s_sub_u32 s88, s88, 0x1800
	s_subb_u32 s89, s89, 0
	v_and_b32_e32 v157, 15, v164
	v_cmp_eq_u32_e32 vcc, 15, v157
	s_nop 4
	s_and_saveexec_b64 s[48:49], vcc
	global_store_dwordx4 v156, v[14:17], s[88:89] offset:0
	global_store_dwordx4 v156, v[10:13], s[88:89] offset:16
	global_store_dwordx4 v156, v[6:9], s[88:89] offset:512
	global_store_dwordx4 v156, v[2:5], s[88:89] offset:528
	s_mov_b64 exec, s[48:49]
	s_branch .Lepi_done
.Lepi_prs:
	v_add_u32_e32 v157, 0xffffc000, v152
	v_lshrrev_b32_e32 v157, 2, v157
	v_mul_u32_u24_e32 v157, 0x1c00, v157
	v_add_u32_e32 v156, v156, v157
	s_add_u32 s88, s36, s46
	s_addc_u32 s89, s37, 0
	s_sub_u32 s88, s88, 0x1800
	s_subb_u32 s89, s89, 0
	v_cvt_pk_bf16_f32 v172, v126, v127
	v_cvt_pk_bf16_f32 v173, v128, v129
	v_cvt_pk_bf16_f32 v174, v122, v123
	v_cvt_pk_bf16_f32 v175, v124, v125
	global_store_dwordx4 v153, v[172:175], s[86:87] offset:0
	v_cvt_pk_bf16_f32 v176, v118, v119
	v_cvt_pk_bf16_f32 v177, v120, v121
	v_cvt_pk_bf16_f32 v178, v114, v115
	v_cvt_pk_bf16_f32 v179, v116, v117
	global_store_dwordx4 v153, v[176:179], s[86:87] offset:256
	s_mov_b64 exec, s[2:3]
	global_store_dwordx4 v156, v[126:129], s[88:89] offset:0
	global_store_dwordx4 v156, v[122:125], s[88:89] offset:16
	global_store_dwordx4 v156, v[118:121], s[88:89] offset:512
	global_store_dwordx4 v156, v[114:117], s[88:89] offset:528
	s_mov_b64 exec, -1
	s_add_u32 s86, s86, 0xe000
	s_addc_u32 s87, s87, 0
	s_add_u32 s88, s88, 0x7000
	s_addc_u32 s89, s89, 0
	v_cvt_pk_bf16_f32 v180, v110, v111
	v_cvt_pk_bf16_f32 v181, v112, v113
	v_cvt_pk_bf16_f32 v182, v106, v107
	v_cvt_pk_bf16_f32 v183, v108, v109
	global_store_dwordx4 v153, v[180:183], s[86:87] offset:0
	v_cvt_pk_bf16_f32 v184, v102, v103
	v_cvt_pk_bf16_f32 v185, v104, v105
	v_cvt_pk_bf16_f32 v186, v98, v99
	v_cvt_pk_bf16_f32 v187, v100, v101
	global_store_dwordx4 v153, v[184:187], s[86:87] offset:256
	s_mov_b64 exec, s[2:3]
	global_store_dwordx4 v156, v[110:113], s[88:89] offset:0
	global_store_dwordx4 v156, v[106:109], s[88:89] offset:16
	global_store_dwordx4 v156, v[102:105], s[88:89] offset:512
	global_store_dwordx4 v156, v[98:101], s[88:89] offset:528
	s_mov_b64 exec, -1
	s_add_u32 s86, s86, 0xe000
	s_addc_u32 s87, s87, 0
	s_add_u32 s88, s88, 0x7000
	s_addc_u32 s89, s89, 0
	v_cvt_pk_bf16_f32 v172, v94, v95
	v_cvt_pk_bf16_f32 v173, v96, v97
	v_cvt_pk_bf16_f32 v174, v90, v91
	v_cvt_pk_bf16_f32 v175, v92, v93
	global_store_dwordx4 v153, v[172:175], s[86:87] offset:0
	v_cvt_pk_bf16_f32 v176, v86, v87
	v_cvt_pk_bf16_f32 v177, v88, v89
	v_cvt_pk_bf16_f32 v178, v82, v83
	v_cvt_pk_bf16_f32 v179, v84, v85
	global_store_dwordx4 v153, v[176:179], s[86:87] offset:256
	s_mov_b64 exec, s[2:3]
	global_store_dwordx4 v156, v[94:97], s[88:89] offset:0
	global_store_dwordx4 v156, v[90:93], s[88:89] offset:16
	global_store_dwordx4 v156, v[86:89], s[88:89] offset:512
	global_store_dwordx4 v156, v[82:85], s[88:89] offset:528
	s_mov_b64 exec, -1
	s_add_u32 s86, s86, 0xe000
	s_addc_u32 s87, s87, 0
	s_add_u32 s88, s88, 0x7000
	s_addc_u32 s89, s89, 0
	v_cvt_pk_bf16_f32 v180, v78, v79
	v_cvt_pk_bf16_f32 v181, v80, v81
	v_cvt_pk_bf16_f32 v182, v74, v75
	v_cvt_pk_bf16_f32 v183, v76, v77
	global_store_dwordx4 v153, v[180:183], s[86:87] offset:0
	v_cvt_pk_bf16_f32 v184, v70, v71
	v_cvt_pk_bf16_f32 v185, v72, v73
	v_cvt_pk_bf16_f32 v186, v66, v67
	v_cvt_pk_bf16_f32 v187, v68, v69
	global_store_dwordx4 v153, v[184:187], s[86:87] offset:256
	s_mov_b64 exec, s[2:3]
	global_store_dwordx4 v156, v[78:81], s[88:89] offset:0
	global_store_dwordx4 v156, v[74:77], s[88:89] offset:16
	global_store_dwordx4 v156, v[70:73], s[88:89] offset:512
	global_store_dwordx4 v156, v[66:69], s[88:89] offset:528
	s_mov_b64 exec, -1
	s_add_u32 s86, s86, 0x46000
	s_addc_u32 s87, s87, 0
	s_add_u32 s88, s88, 0x23000
	s_addc_u32 s89, s89, 0
	v_cvt_pk_bf16_f32 v172, v62, v63
	v_cvt_pk_bf16_f32 v173, v64, v65
	v_cvt_pk_bf16_f32 v174, v58, v59
	v_cvt_pk_bf16_f32 v175, v60, v61
	global_store_dwordx4 v153, v[172:175], s[86:87] offset:0
	v_cvt_pk_bf16_f32 v176, v54, v55
	v_cvt_pk_bf16_f32 v177, v56, v57
	v_cvt_pk_bf16_f32 v178, v50, v51
	v_cvt_pk_bf16_f32 v179, v52, v53
	global_store_dwordx4 v153, v[176:179], s[86:87] offset:256
	s_mov_b64 exec, s[2:3]
	global_store_dwordx4 v156, v[62:65], s[88:89] offset:0
	global_store_dwordx4 v156, v[58:61], s[88:89] offset:16
	global_store_dwordx4 v156, v[54:57], s[88:89] offset:512
	global_store_dwordx4 v156, v[50:53], s[88:89] offset:528
	s_mov_b64 exec, -1
	s_add_u32 s86, s86, 0xe000
	s_addc_u32 s87, s87, 0
	s_add_u32 s88, s88, 0x7000
	s_addc_u32 s89, s89, 0
	v_cvt_pk_bf16_f32 v180, v46, v47
	v_cvt_pk_bf16_f32 v181, v48, v49
	v_cvt_pk_bf16_f32 v182, v42, v43
	v_cvt_pk_bf16_f32 v183, v44, v45
	global_store_dwordx4 v153, v[180:183], s[86:87] offset:0
	v_cvt_pk_bf16_f32 v184, v38, v39
	v_cvt_pk_bf16_f32 v185, v40, v41
	v_cvt_pk_bf16_f32 v186, v34, v35
	v_cvt_pk_bf16_f32 v187, v36, v37
	global_store_dwordx4 v153, v[184:187], s[86:87] offset:256
	s_mov_b64 exec, s[2:3]
	global_store_dwordx4 v156, v[46:49], s[88:89] offset:0
	global_store_dwordx4 v156, v[42:45], s[88:89] offset:16
	global_store_dwordx4 v156, v[38:41], s[88:89] offset:512
	global_store_dwordx4 v156, v[34:37], s[88:89] offset:528
	s_mov_b64 exec, -1
	s_add_u32 s86, s86, 0xe000
	s_addc_u32 s87, s87, 0
	s_add_u32 s88, s88, 0x7000
	s_addc_u32 s89, s89, 0
	v_cvt_pk_bf16_f32 v172, v30, v31
	v_cvt_pk_bf16_f32 v173, v32, v33
	v_cvt_pk_bf16_f32 v174, v26, v27
	v_cvt_pk_bf16_f32 v175, v28, v29
	global_store_dwordx4 v153, v[172:175], s[86:87] offset:0
	v_cvt_pk_bf16_f32 v176, v22, v23
	v_cvt_pk_bf16_f32 v177, v24, v25
	v_cvt_pk_bf16_f32 v178, v18, v19
	v_cvt_pk_bf16_f32 v179, v20, v21
	global_store_dwordx4 v153, v[176:179], s[86:87] offset:256
	s_mov_b64 exec, s[2:3]
	global_store_dwordx4 v156, v[30:33], s[88:89] offset:0
	global_store_dwordx4 v156, v[26:29], s[88:89] offset:16
	global_store_dwordx4 v156, v[22:25], s[88:89] offset:512
	global_store_dwordx4 v156, v[18:21], s[88:89] offset:528
	s_mov_b64 exec, -1
	s_add_u32 s86, s86, 0xe000
	s_addc_u32 s87, s87, 0
	s_add_u32 s88, s88, 0x7000
	s_addc_u32 s89, s89, 0
	v_cvt_pk_bf16_f32 v180, v14, v15
	v_cvt_pk_bf16_f32 v181, v16, v17
	v_cvt_pk_bf16_f32 v182, v10, v11
	v_cvt_pk_bf16_f32 v183, v12, v13
	global_store_dwordx4 v153, v[180:183], s[86:87] offset:0
	v_cvt_pk_bf16_f32 v184, v6, v7
	v_cvt_pk_bf16_f32 v185, v8, v9
	v_cvt_pk_bf16_f32 v186, v2, v3
	v_cvt_pk_bf16_f32 v187, v4, v5
	global_store_dwordx4 v153, v[184:187], s[86:87] offset:256
	s_mov_b64 exec, s[2:3]
	global_store_dwordx4 v156, v[14:17], s[88:89] offset:0
	global_store_dwordx4 v156, v[10:13], s[88:89] offset:16
	global_store_dwordx4 v156, v[6:9], s[88:89] offset:512
	global_store_dwordx4 v156, v[2:5], s[88:89] offset:528
	s_mov_b64 exec, -1
.Lepi_done:
	s_mov_b64 s[90:91], s[42:43]
	s_andn2_b64 vcc, exec, s[4:5]
	s_mov_b64 s[4:5], -1
	s_cbranch_vccnz .LBB0_390
	s_branch .LBB0_767
.LBB0_767:
	s_andn2_b64 vcc, exec, s[0:1]
	s_cbranch_vccnz .LBB0_389
	s_barrier
	s_branch .LBB0_389
.LBB0_773:
	s_waitcnt vmcnt(0)
	v_readlane_b32 s36, v255, 40
	v_readlane_b32 s82, v255, 57
	v_readlane_b32 s83, v255, 56
	v_readlane_b32 s80, v255, 39
	v_readlane_b32 s40, v255, 44
	v_readlane_b32 s41, v255, 45
	v_readlane_b32 s42, v255, 46
	v_readlane_b32 s43, v255, 47
	v_readlane_b32 s46, v255, 50
	v_readlane_b32 s47, v255, 51
	s_barrier
	v_readlane_b32 s37, v255, 41
	v_readlane_b32 s38, v255, 42
	v_readlane_b32 s39, v255, 43
	v_readlane_b32 s44, v255, 48
	v_readlane_b32 s45, v255, 49
	v_readlane_b32 s48, v255, 52
	v_readlane_b32 s49, v255, 53
	v_readlane_b32 s50, v255, 54
	v_readlane_b32 s51, v255, 55
